# FFN1 act stores marked nt (written once, read once 1 ms later) on top of k39
# speedup vs baseline: 1.0019x; 1.0019x over previous
.Lfn_skip_ld:
	v_lshl_add_u32 v159, s18, 8, v155
	v_add_u32_e32 v160, s44, v159
	v_ashrrev_i32_e32 v161, 31, v160
	v_lshl_add_u64 v[160:161], v[160:161], 2, s[6:7]
	global_load_dword v160, v[160:161], off
	v_mov_b32_e32 v162, v120
	v_mov_b32_e32 v163, v124
	v_mov_b32_e32 v124, v121
	v_lshl_or_b32 v148, s19, 7, v157
	v_ashrrev_i32_e32 v149, 31, v148
	s_waitcnt vmcnt(0)
	v_fmamk_f32 v160, v160, 0x3a000000, v153
	v_cmp_gt_f32_e32 vcc, s14, v160
	v_mul_f32_e32 v161, 0x4b800000, v160
	s_nop 0
	v_cndmask_b32_e32 v160, v160, v161, vcc
	v_rsq_f32_e32 v160, v160
	s_nop 0
	v_mul_f32_e32 v161, 0x45800000, v160
	v_cndmask_b32_e32 v160, v160, v161, vcc
	v_pk_mul_f32 v[162:163], v[162:163], v[160:161] op_sel_hi:[1,0]
	s_nop 0
	v_mul_f32_e32 v120, 0xbfb8aa3b, v163
	v_exp_f32_e32 v120, v120
	s_nop 0
	v_add_f32_e32 v120, 1.0, v120
	v_rcp_f32_e32 v120, v120
	s_nop 0
	v_mul_f32_e32 v120, v163, v120
	v_mul_f32_e32 v161, v162, v120
	v_pk_mul_f32 v[120:121], v[124:125], v[160:161] op_sel_hi:[1,0]
	s_nop 0
	v_mul_f32_e32 v124, 0xbfb8aa3b, v121
	v_exp_f32_e32 v124, v124
	s_nop 0
	v_add_f32_e32 v124, 1.0, v124
	v_rcp_f32_e32 v124, v124
	s_nop 0
	v_mul_f32_e32 v121, v121, v124
	v_mul_f32_e32 v124, v120, v121
	v_mov_b32_e32 v120, v122
	v_mov_b32_e32 v121, v126
	v_pk_mul_f32 v[120:121], v[120:121], v[160:161] op_sel_hi:[1,0]
	v_mov_b32_e32 v126, v123
	v_mul_f32_e32 v122, 0xbfb8aa3b, v121
	v_exp_f32_e32 v122, v122
	s_nop 0
	v_add_f32_e32 v122, 1.0, v122
	v_rcp_f32_e32 v122, v122
	s_nop 0
	v_mul_f32_e32 v121, v121, v122
	v_mul_f32_e32 v122, v120, v121
	v_pk_mul_f32 v[120:121], v[126:127], v[160:161] op_sel_hi:[1,0]
	s_nop 0
	v_mul_f32_e32 v123, 0xbfb8aa3b, v121
	v_exp_f32_e32 v123, v123
	s_nop 0
	v_add_f32_e32 v123, 1.0, v123
	v_rcp_f32_e32 v123, v123
	s_nop 0
	v_mul_f32_e32 v121, v121, v123
	v_mul_f32_e32 v123, v120, v121
	v_mov_b32_e32 v120, v112
	v_mov_b32_e32 v121, v116
	v_pk_mul_f32 v[120:121], v[120:121], v[160:161] op_sel_hi:[1,0]
	v_mov_b32_e32 v116, v113
	v_mul_f32_e32 v112, 0xbfb8aa3b, v121
	v_exp_f32_e32 v112, v112
	s_nop 0
	v_add_f32_e32 v112, 1.0, v112
	v_rcp_f32_e32 v112, v112
	s_nop 0
	v_mul_f32_e32 v112, v121, v112
	v_mul_f32_e32 v120, v120, v112
	v_pk_mul_f32 v[112:113], v[116:117], v[160:161] op_sel_hi:[1,0]
	s_nop 0
	v_mul_f32_e32 v116, 0xbfb8aa3b, v113
	v_exp_f32_e32 v116, v116
	s_nop 0
	v_add_f32_e32 v116, 1.0, v116
	v_rcp_f32_e32 v116, v116
	s_nop 0
	v_mul_f32_e32 v113, v113, v116
	v_mul_f32_e32 v121, v112, v113
	v_mov_b32_e32 v112, v114
	v_mov_b32_e32 v113, v118
	v_pk_mul_f32 v[112:113], v[112:113], v[160:161] op_sel_hi:[1,0]
	v_mov_b32_e32 v118, v115
	v_mul_f32_e32 v114, 0xbfb8aa3b, v113
	v_exp_f32_e32 v114, v114
	v_cvt_pk_bf16_f32 v116, v161, v124
	v_cvt_pk_bf16_f32 v117, v122, v123
	s_nop 0
	v_add_f32_e32 v114, 1.0, v114
	v_rcp_f32_e32 v114, v114
	s_nop 0
	v_mul_f32_e32 v113, v113, v114
	v_mul_f32_e32 v114, v112, v113
	v_pk_mul_f32 v[112:113], v[118:119], v[160:161] op_sel_hi:[1,0]
	v_cvt_pk_bf16_f32 v118, v120, v121
	s_nop 0
	v_mul_f32_e32 v115, 0xbfb8aa3b, v113
	v_exp_f32_e32 v115, v115
	s_nop 0
	v_add_f32_e32 v115, 1.0, v115
	v_rcp_f32_e32 v115, v115
	s_nop 0
	v_mul_f32_e32 v113, v113, v115
	v_mul_f32_e32 v112, v112, v113
	v_cvt_pk_bf16_f32 v119, v114, v112
	v_mov_b64_e32 v[112:113], s[4:5]
	v_mad_i64_i32 v[120:121], s[18:19], v159, s15, v[112:113]
	v_lshlrev_b64 v[114:115], 1, v[148:149]
	v_lshl_add_u64 v[120:121], v[120:121], 0, v[114:115]
	global_store_dwordx4 v[120:121], v[116:119], off nt
	v_or_b32_e32 v120, 16, v159
	s_nop 0
	v_add_u32_e32 v116, s44, v120
	v_ashrrev_i32_e32 v117, 31, v116
	v_lshl_add_u64 v[116:117], v[116:117], 2, s[6:7]
	global_load_dword v116, v[116:117], off
	v_mov_b32_e32 v118, v104
	v_mov_b32_e32 v119, v108
	v_mov_b32_e32 v108, v105
	s_waitcnt vmcnt(0)
	v_fmamk_f32 v116, v116, 0x3a000000, v153
	v_cmp_gt_f32_e32 vcc, s14, v116
	v_mul_f32_e32 v117, 0x4b800000, v116
	s_nop 0
	v_cndmask_b32_e32 v116, v116, v117, vcc
	v_rsq_f32_e32 v116, v116
	s_nop 0
	v_mul_f32_e32 v117, 0x45800000, v116
	v_cndmask_b32_e32 v116, v116, v117, vcc
	v_pk_mul_f32 v[118:119], v[118:119], v[116:117] op_sel_hi:[1,0]
	s_nop 0
	v_mul_f32_e32 v104, 0xbfb8aa3b, v119
	v_exp_f32_e32 v104, v104
	s_nop 0
	v_add_f32_e32 v104, 1.0, v104
	v_rcp_f32_e32 v104, v104
	s_nop 0
	v_mul_f32_e32 v104, v119, v104
	v_mul_f32_e32 v117, v118, v104
	v_pk_mul_f32 v[104:105], v[108:109], v[116:117] op_sel_hi:[1,0]
	s_nop 0
	v_mul_f32_e32 v108, 0xbfb8aa3b, v105
	v_exp_f32_e32 v108, v108
	s_nop 0
	v_add_f32_e32 v108, 1.0, v108
	v_rcp_f32_e32 v108, v108
	s_nop 0
	v_mul_f32_e32 v105, v105, v108
	v_mul_f32_e32 v108, v104, v105
	v_mov_b32_e32 v104, v106
	v_mov_b32_e32 v105, v110
	v_pk_mul_f32 v[104:105], v[104:105], v[116:117] op_sel_hi:[1,0]
	v_mov_b32_e32 v110, v107
	v_mul_f32_e32 v106, 0xbfb8aa3b, v105
	v_exp_f32_e32 v106, v106
	s_nop 0
	v_add_f32_e32 v106, 1.0, v106
	v_rcp_f32_e32 v106, v106
	s_nop 0
	v_mul_f32_e32 v105, v105, v106
	v_mul_f32_e32 v106, v104, v105
	v_pk_mul_f32 v[104:105], v[110:111], v[116:117] op_sel_hi:[1,0]
	s_nop 0
	v_mul_f32_e32 v107, 0xbfb8aa3b, v105
	v_exp_f32_e32 v107, v107
	s_nop 0
	v_add_f32_e32 v107, 1.0, v107
	v_rcp_f32_e32 v107, v107
	s_nop 0
	v_mul_f32_e32 v105, v105, v107
	v_mul_f32_e32 v107, v104, v105
	v_mov_b32_e32 v104, v96
	v_mov_b32_e32 v105, v100
	v_pk_mul_f32 v[104:105], v[104:105], v[116:117] op_sel_hi:[1,0]
	v_mov_b32_e32 v100, v97
	v_mul_f32_e32 v96, 0xbfb8aa3b, v105
	v_exp_f32_e32 v96, v96
	s_nop 0
	v_add_f32_e32 v96, 1.0, v96
	v_rcp_f32_e32 v96, v96
	s_nop 0
	v_mul_f32_e32 v96, v105, v96
	v_mul_f32_e32 v104, v104, v96
	v_pk_mul_f32 v[96:97], v[100:101], v[116:117] op_sel_hi:[1,0]
	s_nop 0
	v_mul_f32_e32 v100, 0xbfb8aa3b, v97
	v_exp_f32_e32 v100, v100
	s_nop 0
	v_add_f32_e32 v100, 1.0, v100
	v_rcp_f32_e32 v100, v100
	s_nop 0
	v_mul_f32_e32 v97, v97, v100
	v_mul_f32_e32 v100, v96, v97
	v_mov_b32_e32 v96, v98
	v_mov_b32_e32 v97, v102
	v_pk_mul_f32 v[96:97], v[96:97], v[116:117] op_sel_hi:[1,0]
	v_mov_b32_e32 v102, v99
	v_mul_f32_e32 v98, 0xbfb8aa3b, v97
	v_exp_f32_e32 v98, v98
	s_nop 0
	v_add_f32_e32 v98, 1.0, v98
	v_rcp_f32_e32 v98, v98
	s_nop 0
	v_mul_f32_e32 v97, v97, v98
	v_mul_f32_e32 v101, v96, v97
	v_pk_mul_f32 v[96:97], v[102:103], v[116:117] op_sel_hi:[1,0]
	s_nop 0
	v_mul_f32_e32 v98, 0xbfb8aa3b, v97
	v_exp_f32_e32 v98, v98
	s_nop 0
	v_add_f32_e32 v98, 1.0, v98
	v_rcp_f32_e32 v98, v98
	s_nop 0
	v_mul_f32_e32 v97, v97, v98
	v_mul_f32_e32 v99, v96, v97
	v_cvt_pk_bf16_f32 v96, v117, v108
	v_cvt_pk_bf16_f32 v97, v106, v107
	v_cvt_pk_bf16_f32 v98, v104, v100
	v_cvt_pk_bf16_f32 v99, v101, v99
	v_mad_i64_i32 v[100:101], s[18:19], v120, s15, v[112:113]
	v_lshl_add_u64 v[100:101], v[100:101], 0, v[114:115]
	global_store_dwordx4 v[100:101], v[96:99], off nt
	v_or_b32_e32 v100, 32, v159
	s_nop 0
	v_add_u32_e32 v96, s44, v100
	v_ashrrev_i32_e32 v97, 31, v96
	v_lshl_add_u64 v[96:97], v[96:97], 2, s[6:7]
	global_load_dword v96, v[96:97], off
	v_mov_b32_e32 v98, v88
	v_mov_b32_e32 v99, v92
	v_mov_b32_e32 v92, v89
	s_waitcnt vmcnt(0)
	v_fmamk_f32 v96, v96, 0x3a000000, v153
	v_cmp_gt_f32_e32 vcc, s14, v96
	v_mul_f32_e32 v97, 0x4b800000, v96
	s_nop 0
	v_cndmask_b32_e32 v96, v96, v97, vcc
	v_rsq_f32_e32 v96, v96
	s_nop 0
	v_mul_f32_e32 v97, 0x45800000, v96
	v_cndmask_b32_e32 v96, v96, v97, vcc
	v_pk_mul_f32 v[98:99], v[98:99], v[96:97] op_sel_hi:[1,0]
	s_nop 0
	v_mul_f32_e32 v88, 0xbfb8aa3b, v99
	v_exp_f32_e32 v88, v88
	s_nop 0
	v_add_f32_e32 v88, 1.0, v88
	v_rcp_f32_e32 v88, v88
	s_nop 0
	v_mul_f32_e32 v88, v99, v88
	v_mul_f32_e32 v97, v98, v88
	v_pk_mul_f32 v[88:89], v[92:93], v[96:97] op_sel_hi:[1,0]
	s_nop 0
	v_mul_f32_e32 v92, 0xbfb8aa3b, v89
	v_exp_f32_e32 v92, v92
	s_nop 0
	v_add_f32_e32 v92, 1.0, v92
	v_rcp_f32_e32 v92, v92
	s_nop 0
	v_mul_f32_e32 v89, v89, v92
	v_mul_f32_e32 v92, v88, v89
	v_mov_b32_e32 v88, v90
	v_mov_b32_e32 v89, v94
	v_pk_mul_f32 v[88:89], v[88:89], v[96:97] op_sel_hi:[1,0]
	v_mov_b32_e32 v94, v91
	v_mul_f32_e32 v90, 0xbfb8aa3b, v89
	v_exp_f32_e32 v90, v90
	s_nop 0
	v_add_f32_e32 v90, 1.0, v90
	v_rcp_f32_e32 v90, v90
	s_nop 0
	v_mul_f32_e32 v89, v89, v90
	v_mul_f32_e32 v90, v88, v89
	v_pk_mul_f32 v[88:89], v[94:95], v[96:97] op_sel_hi:[1,0]
	s_nop 0
	v_mul_f32_e32 v91, 0xbfb8aa3b, v89
	v_exp_f32_e32 v91, v91
	s_nop 0
	v_add_f32_e32 v91, 1.0, v91
	v_rcp_f32_e32 v91, v91
	s_nop 0
	v_mul_f32_e32 v89, v89, v91
	v_mul_f32_e32 v91, v88, v89
	v_mov_b32_e32 v88, v80
	v_mov_b32_e32 v89, v84
	v_pk_mul_f32 v[88:89], v[88:89], v[96:97] op_sel_hi:[1,0]
	v_mov_b32_e32 v84, v81
	v_mul_f32_e32 v80, 0xbfb8aa3b, v89
	v_exp_f32_e32 v80, v80
	s_nop 0
	v_add_f32_e32 v80, 1.0, v80
	v_rcp_f32_e32 v80, v80
	s_nop 0
	v_mul_f32_e32 v80, v89, v80
	v_mul_f32_e32 v88, v88, v80
	v_pk_mul_f32 v[80:81], v[84:85], v[96:97] op_sel_hi:[1,0]
	s_nop 0
	v_mul_f32_e32 v84, 0xbfb8aa3b, v81
	v_exp_f32_e32 v84, v84
	s_nop 0
	v_add_f32_e32 v84, 1.0, v84
	v_rcp_f32_e32 v84, v84
	s_nop 0
	v_mul_f32_e32 v81, v81, v84
	v_mul_f32_e32 v84, v80, v81
	v_mov_b32_e32 v80, v82
	v_mov_b32_e32 v81, v86
	v_pk_mul_f32 v[80:81], v[80:81], v[96:97] op_sel_hi:[1,0]
	v_mov_b32_e32 v86, v83
	v_mul_f32_e32 v82, 0xbfb8aa3b, v81
	v_exp_f32_e32 v82, v82
	s_nop 0
	v_add_f32_e32 v82, 1.0, v82
	v_rcp_f32_e32 v82, v82
	s_nop 0
	v_mul_f32_e32 v81, v81, v82
	v_mul_f32_e32 v85, v80, v81
	v_pk_mul_f32 v[80:81], v[86:87], v[96:97] op_sel_hi:[1,0]
	s_nop 0
	v_mul_f32_e32 v82, 0xbfb8aa3b, v81
	v_exp_f32_e32 v82, v82
	s_nop 0
	v_add_f32_e32 v82, 1.0, v82
	v_rcp_f32_e32 v82, v82
	s_nop 0
	v_mul_f32_e32 v81, v81, v82
	v_mul_f32_e32 v83, v80, v81
	v_cvt_pk_bf16_f32 v80, v97, v92
	v_cvt_pk_bf16_f32 v81, v90, v91
	v_cvt_pk_bf16_f32 v82, v88, v84
	v_cvt_pk_bf16_f32 v83, v85, v83
	v_mad_i64_i32 v[84:85], s[18:19], v100, s15, v[112:113]
	v_lshl_add_u64 v[84:85], v[84:85], 0, v[114:115]
	global_store_dwordx4 v[84:85], v[80:83], off nt
	v_or_b32_e32 v84, 48, v159
	s_nop 0
	v_add_u32_e32 v80, s44, v84
	v_ashrrev_i32_e32 v81, 31, v80
	v_lshl_add_u64 v[80:81], v[80:81], 2, s[6:7]
	global_load_dword v80, v[80:81], off
	v_mov_b32_e32 v82, v72
	v_mov_b32_e32 v83, v76
	v_mov_b32_e32 v76, v73
	s_waitcnt vmcnt(0)
	v_fmamk_f32 v80, v80, 0x3a000000, v153
	v_cmp_gt_f32_e32 vcc, s14, v80
	v_mul_f32_e32 v81, 0x4b800000, v80
	s_nop 0
	v_cndmask_b32_e32 v80, v80, v81, vcc
	v_rsq_f32_e32 v80, v80
	s_nop 0
	v_mul_f32_e32 v81, 0x45800000, v80
	v_cndmask_b32_e32 v80, v80, v81, vcc
	v_pk_mul_f32 v[82:83], v[82:83], v[80:81] op_sel_hi:[1,0]
	s_nop 0
	v_mul_f32_e32 v72, 0xbfb8aa3b, v83
	v_exp_f32_e32 v72, v72
	s_nop 0
	v_add_f32_e32 v72, 1.0, v72
	v_rcp_f32_e32 v72, v72
	s_nop 0
	v_mul_f32_e32 v72, v83, v72
	v_mul_f32_e32 v81, v82, v72
	v_pk_mul_f32 v[72:73], v[76:77], v[80:81] op_sel_hi:[1,0]
	s_nop 0
	v_mul_f32_e32 v76, 0xbfb8aa3b, v73
	v_exp_f32_e32 v76, v76
	s_nop 0
	v_add_f32_e32 v76, 1.0, v76
	v_rcp_f32_e32 v76, v76
	s_nop 0
	v_mul_f32_e32 v73, v73, v76
	v_mul_f32_e32 v76, v72, v73
	v_mov_b32_e32 v72, v74
	v_mov_b32_e32 v73, v78
	v_pk_mul_f32 v[72:73], v[72:73], v[80:81] op_sel_hi:[1,0]
	v_mov_b32_e32 v78, v75
	v_mul_f32_e32 v74, 0xbfb8aa3b, v73
	v_exp_f32_e32 v74, v74
	s_nop 0
	v_add_f32_e32 v74, 1.0, v74
	v_rcp_f32_e32 v74, v74
	s_nop 0
	v_mul_f32_e32 v73, v73, v74
	v_mul_f32_e32 v74, v72, v73
	v_pk_mul_f32 v[72:73], v[78:79], v[80:81] op_sel_hi:[1,0]
	s_nop 0
	v_mul_f32_e32 v75, 0xbfb8aa3b, v73
	v_exp_f32_e32 v75, v75
	s_nop 0
	v_add_f32_e32 v75, 1.0, v75
	v_rcp_f32_e32 v75, v75
	s_nop 0
	v_mul_f32_e32 v73, v73, v75
	v_mul_f32_e32 v75, v72, v73
	v_mov_b32_e32 v72, v64
	v_mov_b32_e32 v73, v68
	v_pk_mul_f32 v[72:73], v[72:73], v[80:81] op_sel_hi:[1,0]
	v_mov_b32_e32 v68, v65
	v_mul_f32_e32 v64, 0xbfb8aa3b, v73
	v_exp_f32_e32 v64, v64
	s_nop 0
	v_add_f32_e32 v64, 1.0, v64
	v_rcp_f32_e32 v64, v64
	s_nop 0
	v_mul_f32_e32 v64, v73, v64
	v_mul_f32_e32 v72, v72, v64
	v_pk_mul_f32 v[64:65], v[68:69], v[80:81] op_sel_hi:[1,0]
	s_nop 0
	v_mul_f32_e32 v68, 0xbfb8aa3b, v65
	v_exp_f32_e32 v68, v68
	s_nop 0
	v_add_f32_e32 v68, 1.0, v68
	v_rcp_f32_e32 v68, v68
	s_nop 0
	v_mul_f32_e32 v65, v65, v68
	v_mul_f32_e32 v68, v64, v65
	v_mov_b32_e32 v64, v66
	v_mov_b32_e32 v65, v70
	v_pk_mul_f32 v[64:65], v[64:65], v[80:81] op_sel_hi:[1,0]
	v_mov_b32_e32 v70, v67
	v_mul_f32_e32 v66, 0xbfb8aa3b, v65
	v_exp_f32_e32 v66, v66
	s_nop 0
	v_add_f32_e32 v66, 1.0, v66
	v_rcp_f32_e32 v66, v66
	s_nop 0
	v_mul_f32_e32 v65, v65, v66
	v_mul_f32_e32 v69, v64, v65
	v_pk_mul_f32 v[64:65], v[70:71], v[80:81] op_sel_hi:[1,0]
	s_nop 0
	v_mul_f32_e32 v66, 0xbfb8aa3b, v65
	v_exp_f32_e32 v66, v66
	s_nop 0
	v_add_f32_e32 v66, 1.0, v66
	v_rcp_f32_e32 v66, v66
	s_nop 0
	v_mul_f32_e32 v65, v65, v66
	v_mul_f32_e32 v67, v64, v65
	v_cvt_pk_bf16_f32 v64, v81, v76
	v_cvt_pk_bf16_f32 v65, v74, v75
	v_cvt_pk_bf16_f32 v66, v72, v68
	v_cvt_pk_bf16_f32 v67, v69, v67
	v_mad_i64_i32 v[68:69], s[18:19], v84, s15, v[112:113]
	v_lshl_add_u64 v[68:69], v[68:69], 0, v[114:115]
	global_store_dwordx4 v[68:69], v[64:67], off nt
	v_add_u32_e32 v68, 0x80, v159
	s_nop 0
	v_add_u32_e32 v64, s44, v68
	v_ashrrev_i32_e32 v65, 31, v64
	v_lshl_add_u64 v[64:65], v[64:65], 2, s[6:7]
	global_load_dword v64, v[64:65], off
	v_mov_b32_e32 v66, v56
	v_mov_b32_e32 v67, v60
	v_mov_b32_e32 v60, v57
	s_waitcnt vmcnt(0)
	v_fmamk_f32 v64, v64, 0x3a000000, v153
	v_cmp_gt_f32_e32 vcc, s14, v64
	v_mul_f32_e32 v65, 0x4b800000, v64
	s_nop 0
	v_cndmask_b32_e32 v64, v64, v65, vcc
	v_rsq_f32_e32 v64, v64
	s_nop 0
	v_mul_f32_e32 v65, 0x45800000, v64
	v_cndmask_b32_e32 v64, v64, v65, vcc
	v_pk_mul_f32 v[66:67], v[66:67], v[64:65] op_sel_hi:[1,0]
	s_nop 0
	v_mul_f32_e32 v56, 0xbfb8aa3b, v67
	v_exp_f32_e32 v56, v56
	s_nop 0
	v_add_f32_e32 v56, 1.0, v56
	v_rcp_f32_e32 v56, v56
	s_nop 0
	v_mul_f32_e32 v56, v67, v56
	v_mul_f32_e32 v65, v66, v56
	v_pk_mul_f32 v[56:57], v[60:61], v[64:65] op_sel_hi:[1,0]
	s_nop 0
	v_mul_f32_e32 v60, 0xbfb8aa3b, v57
	v_exp_f32_e32 v60, v60
	s_nop 0
	v_add_f32_e32 v60, 1.0, v60
	v_rcp_f32_e32 v60, v60
	s_nop 0
	v_mul_f32_e32 v57, v57, v60
	v_mul_f32_e32 v60, v56, v57
	v_mov_b32_e32 v56, v58
	v_mov_b32_e32 v57, v62
	v_pk_mul_f32 v[56:57], v[56:57], v[64:65] op_sel_hi:[1,0]
	v_mov_b32_e32 v62, v59
	v_mul_f32_e32 v58, 0xbfb8aa3b, v57
	v_exp_f32_e32 v58, v58
	s_nop 0
	v_add_f32_e32 v58, 1.0, v58
	v_rcp_f32_e32 v58, v58
	s_nop 0
	v_mul_f32_e32 v57, v57, v58
	v_mul_f32_e32 v58, v56, v57
	v_pk_mul_f32 v[56:57], v[62:63], v[64:65] op_sel_hi:[1,0]
	s_nop 0
	v_mul_f32_e32 v59, 0xbfb8aa3b, v57
	v_exp_f32_e32 v59, v59
	s_nop 0
	v_add_f32_e32 v59, 1.0, v59
	v_rcp_f32_e32 v59, v59
	s_nop 0
	v_mul_f32_e32 v57, v57, v59
	v_mul_f32_e32 v59, v56, v57
	v_mov_b32_e32 v56, v48
	v_mov_b32_e32 v57, v52
	v_pk_mul_f32 v[56:57], v[56:57], v[64:65] op_sel_hi:[1,0]
	v_mov_b32_e32 v52, v49
	v_mul_f32_e32 v48, 0xbfb8aa3b, v57
	v_exp_f32_e32 v48, v48
	s_nop 0
	v_add_f32_e32 v48, 1.0, v48
	v_rcp_f32_e32 v48, v48
	s_nop 0
	v_mul_f32_e32 v48, v57, v48
	v_mul_f32_e32 v56, v56, v48
	v_pk_mul_f32 v[48:49], v[52:53], v[64:65] op_sel_hi:[1,0]
	s_nop 0
	v_mul_f32_e32 v52, 0xbfb8aa3b, v49
	v_exp_f32_e32 v52, v52
	s_nop 0
	v_add_f32_e32 v52, 1.0, v52
	v_rcp_f32_e32 v52, v52
	s_nop 0
	v_mul_f32_e32 v49, v49, v52
	v_mul_f32_e32 v52, v48, v49
	v_mov_b32_e32 v48, v50
	v_mov_b32_e32 v49, v54
	v_pk_mul_f32 v[48:49], v[48:49], v[64:65] op_sel_hi:[1,0]
	v_mov_b32_e32 v54, v51
	v_mul_f32_e32 v50, 0xbfb8aa3b, v49
	v_exp_f32_e32 v50, v50
	s_nop 0
	v_add_f32_e32 v50, 1.0, v50
	v_rcp_f32_e32 v50, v50
	s_nop 0
	v_mul_f32_e32 v49, v49, v50
	v_mul_f32_e32 v53, v48, v49
	v_pk_mul_f32 v[48:49], v[54:55], v[64:65] op_sel_hi:[1,0]
	s_nop 0
	v_mul_f32_e32 v50, 0xbfb8aa3b, v49
	v_exp_f32_e32 v50, v50
	s_nop 0
	v_add_f32_e32 v50, 1.0, v50
	v_rcp_f32_e32 v50, v50
	s_nop 0
	v_mul_f32_e32 v49, v49, v50
	v_mul_f32_e32 v51, v48, v49
	v_cvt_pk_bf16_f32 v48, v65, v60
	v_cvt_pk_bf16_f32 v49, v58, v59
	v_cvt_pk_bf16_f32 v50, v56, v52
	v_cvt_pk_bf16_f32 v51, v53, v51
	v_mad_i64_i32 v[52:53], s[18:19], v68, s15, v[112:113]
	v_lshl_add_u64 v[52:53], v[52:53], 0, v[114:115]
	global_store_dwordx4 v[52:53], v[48:51], off nt
	v_add_u32_e32 v52, 0x90, v159
	s_nop 0
	v_add_u32_e32 v48, s44, v52
	v_ashrrev_i32_e32 v49, 31, v48
	v_lshl_add_u64 v[48:49], v[48:49], 2, s[6:7]
	global_load_dword v48, v[48:49], off
	v_mov_b32_e32 v50, v40
	v_mov_b32_e32 v51, v44
	v_mov_b32_e32 v44, v41
	s_waitcnt vmcnt(0)
	v_fmamk_f32 v48, v48, 0x3a000000, v153
	v_cmp_gt_f32_e32 vcc, s14, v48
	v_mul_f32_e32 v49, 0x4b800000, v48
	s_nop 0
	v_cndmask_b32_e32 v48, v48, v49, vcc
	v_rsq_f32_e32 v48, v48
	s_nop 0
	v_mul_f32_e32 v49, 0x45800000, v48
	v_cndmask_b32_e32 v48, v48, v49, vcc
	v_pk_mul_f32 v[50:51], v[50:51], v[48:49] op_sel_hi:[1,0]
	s_nop 0
	v_mul_f32_e32 v40, 0xbfb8aa3b, v51
	v_exp_f32_e32 v40, v40
	s_nop 0
	v_add_f32_e32 v40, 1.0, v40
	v_rcp_f32_e32 v40, v40
	s_nop 0
	v_mul_f32_e32 v40, v51, v40
	v_mul_f32_e32 v49, v50, v40
	v_pk_mul_f32 v[40:41], v[44:45], v[48:49] op_sel_hi:[1,0]
	s_nop 0
	v_mul_f32_e32 v44, 0xbfb8aa3b, v41
	v_exp_f32_e32 v44, v44
	s_nop 0
	v_add_f32_e32 v44, 1.0, v44
	v_rcp_f32_e32 v44, v44
	s_nop 0
	v_mul_f32_e32 v41, v41, v44
	v_mul_f32_e32 v44, v40, v41
	v_mov_b32_e32 v40, v42
	v_mov_b32_e32 v41, v46
	v_pk_mul_f32 v[40:41], v[40:41], v[48:49] op_sel_hi:[1,0]
	v_mov_b32_e32 v46, v43
	v_mul_f32_e32 v42, 0xbfb8aa3b, v41
	v_exp_f32_e32 v42, v42
	s_nop 0
	v_add_f32_e32 v42, 1.0, v42
	v_rcp_f32_e32 v42, v42
	s_nop 0
	v_mul_f32_e32 v41, v41, v42
	v_mul_f32_e32 v42, v40, v41
	v_pk_mul_f32 v[40:41], v[46:47], v[48:49] op_sel_hi:[1,0]
	s_nop 0
	v_mul_f32_e32 v43, 0xbfb8aa3b, v41
	v_exp_f32_e32 v43, v43
	s_nop 0
	v_add_f32_e32 v43, 1.0, v43
	v_rcp_f32_e32 v43, v43
	s_nop 0
	v_mul_f32_e32 v41, v41, v43
	v_mul_f32_e32 v43, v40, v41
	v_mov_b32_e32 v40, v32
	v_mov_b32_e32 v41, v36
	v_pk_mul_f32 v[40:41], v[40:41], v[48:49] op_sel_hi:[1,0]
	v_mov_b32_e32 v36, v33
	v_mul_f32_e32 v32, 0xbfb8aa3b, v41
	v_exp_f32_e32 v32, v32
	s_nop 0
	v_add_f32_e32 v32, 1.0, v32
	v_rcp_f32_e32 v32, v32
	s_nop 0
	v_mul_f32_e32 v32, v41, v32
	v_mul_f32_e32 v40, v40, v32
	v_pk_mul_f32 v[32:33], v[36:37], v[48:49] op_sel_hi:[1,0]
	s_nop 0
	v_mul_f32_e32 v36, 0xbfb8aa3b, v33
	v_exp_f32_e32 v36, v36
	s_nop 0
	v_add_f32_e32 v36, 1.0, v36
	v_rcp_f32_e32 v36, v36
	s_nop 0
	v_mul_f32_e32 v33, v33, v36
	v_mul_f32_e32 v36, v32, v33
	v_mov_b32_e32 v32, v34
	v_mov_b32_e32 v33, v38
	v_pk_mul_f32 v[32:33], v[32:33], v[48:49] op_sel_hi:[1,0]
	v_mov_b32_e32 v38, v35
	v_mul_f32_e32 v34, 0xbfb8aa3b, v33
	v_exp_f32_e32 v34, v34
	s_nop 0
	v_add_f32_e32 v34, 1.0, v34
	v_rcp_f32_e32 v34, v34
	s_nop 0
	v_mul_f32_e32 v33, v33, v34
	v_mul_f32_e32 v37, v32, v33
	v_pk_mul_f32 v[32:33], v[38:39], v[48:49] op_sel_hi:[1,0]
	s_nop 0
	v_mul_f32_e32 v34, 0xbfb8aa3b, v33
	v_exp_f32_e32 v34, v34
	s_nop 0
	v_add_f32_e32 v34, 1.0, v34
	v_rcp_f32_e32 v34, v34
	s_nop 0
	v_mul_f32_e32 v33, v33, v34
	v_mul_f32_e32 v35, v32, v33
	v_cvt_pk_bf16_f32 v32, v49, v44
	v_cvt_pk_bf16_f32 v33, v42, v43
	v_cvt_pk_bf16_f32 v34, v40, v36
	v_cvt_pk_bf16_f32 v35, v37, v35
	v_mad_i64_i32 v[36:37], s[18:19], v52, s15, v[112:113]
	v_lshl_add_u64 v[36:37], v[36:37], 0, v[114:115]
	global_store_dwordx4 v[36:37], v[32:35], off nt
	v_add_u32_e32 v36, 0xa0, v159
	s_nop 0
	v_add_u32_e32 v32, s44, v36
	v_ashrrev_i32_e32 v33, 31, v32
	v_lshl_add_u64 v[32:33], v[32:33], 2, s[6:7]
	global_load_dword v32, v[32:33], off
	v_mov_b32_e32 v34, v24
	v_mov_b32_e32 v35, v28
	v_mov_b32_e32 v28, v25
	s_waitcnt vmcnt(0)
	v_fmamk_f32 v32, v32, 0x3a000000, v153
	v_cmp_gt_f32_e32 vcc, s14, v32
	v_mul_f32_e32 v33, 0x4b800000, v32
	s_nop 0
	v_cndmask_b32_e32 v32, v32, v33, vcc
	v_rsq_f32_e32 v32, v32
	s_nop 0
	v_mul_f32_e32 v33, 0x45800000, v32
	v_cndmask_b32_e32 v32, v32, v33, vcc
	v_pk_mul_f32 v[34:35], v[34:35], v[32:33] op_sel_hi:[1,0]
	s_nop 0
	v_mul_f32_e32 v24, 0xbfb8aa3b, v35
	v_exp_f32_e32 v24, v24
	s_nop 0
	v_add_f32_e32 v24, 1.0, v24
	v_rcp_f32_e32 v24, v24
	s_nop 0
	v_mul_f32_e32 v24, v35, v24
	v_mul_f32_e32 v33, v34, v24
	v_pk_mul_f32 v[24:25], v[28:29], v[32:33] op_sel_hi:[1,0]
	s_nop 0
	v_mul_f32_e32 v28, 0xbfb8aa3b, v25
	v_exp_f32_e32 v28, v28
	s_nop 0
	v_add_f32_e32 v28, 1.0, v28
	v_rcp_f32_e32 v28, v28
	s_nop 0
	v_mul_f32_e32 v25, v25, v28
	v_mul_f32_e32 v28, v24, v25
	v_mov_b32_e32 v24, v26
	v_mov_b32_e32 v25, v30
	v_pk_mul_f32 v[24:25], v[24:25], v[32:33] op_sel_hi:[1,0]
	v_mov_b32_e32 v30, v27
	v_mul_f32_e32 v26, 0xbfb8aa3b, v25
	v_exp_f32_e32 v26, v26
	s_nop 0
	v_add_f32_e32 v26, 1.0, v26
	v_rcp_f32_e32 v26, v26
	s_nop 0
	v_mul_f32_e32 v25, v25, v26
	v_mul_f32_e32 v26, v24, v25
	v_pk_mul_f32 v[24:25], v[30:31], v[32:33] op_sel_hi:[1,0]
	s_nop 0
	v_mul_f32_e32 v27, 0xbfb8aa3b, v25
	v_exp_f32_e32 v27, v27
	s_nop 0
	v_add_f32_e32 v27, 1.0, v27
	v_rcp_f32_e32 v27, v27
	s_nop 0
	v_mul_f32_e32 v25, v25, v27
	v_mul_f32_e32 v27, v24, v25
	v_mov_b32_e32 v24, v16
	v_mov_b32_e32 v25, v20
	v_pk_mul_f32 v[24:25], v[24:25], v[32:33] op_sel_hi:[1,0]
	v_mov_b32_e32 v20, v17
	v_mul_f32_e32 v16, 0xbfb8aa3b, v25
	v_exp_f32_e32 v16, v16
	s_nop 0
	v_add_f32_e32 v16, 1.0, v16
	v_rcp_f32_e32 v16, v16
	s_nop 0
	v_mul_f32_e32 v16, v25, v16
	v_mul_f32_e32 v24, v24, v16
	v_pk_mul_f32 v[16:17], v[20:21], v[32:33] op_sel_hi:[1,0]
	s_nop 0
	v_mul_f32_e32 v20, 0xbfb8aa3b, v17
	v_exp_f32_e32 v20, v20
	s_nop 0
	v_add_f32_e32 v20, 1.0, v20
	v_rcp_f32_e32 v20, v20
	s_nop 0
	v_mul_f32_e32 v17, v17, v20
	v_mul_f32_e32 v20, v16, v17
	v_mov_b32_e32 v16, v18
	v_mov_b32_e32 v17, v22
	v_pk_mul_f32 v[16:17], v[16:17], v[32:33] op_sel_hi:[1,0]
	v_mov_b32_e32 v22, v19
	v_mul_f32_e32 v18, 0xbfb8aa3b, v17
	v_exp_f32_e32 v18, v18
	s_nop 0
	v_add_f32_e32 v18, 1.0, v18
	v_rcp_f32_e32 v18, v18
	s_nop 0
	v_mul_f32_e32 v17, v17, v18
	v_mul_f32_e32 v21, v16, v17
	v_pk_mul_f32 v[16:17], v[22:23], v[32:33] op_sel_hi:[1,0]
	s_nop 0
	v_mul_f32_e32 v18, 0xbfb8aa3b, v17
	v_exp_f32_e32 v18, v18
	s_nop 0
	v_add_f32_e32 v18, 1.0, v18
	v_rcp_f32_e32 v18, v18
	s_nop 0
	v_mul_f32_e32 v17, v17, v18
	v_mul_f32_e32 v19, v16, v17
	v_cvt_pk_bf16_f32 v16, v33, v28
	v_cvt_pk_bf16_f32 v17, v26, v27
	v_cvt_pk_bf16_f32 v18, v24, v20
	v_cvt_pk_bf16_f32 v19, v21, v19
	v_mad_i64_i32 v[20:21], s[18:19], v36, s15, v[112:113]
	v_lshl_add_u64 v[20:21], v[20:21], 0, v[114:115]
	global_store_dwordx4 v[20:21], v[16:19], off nt
	v_add_u32_e32 v20, 0xb0, v159
	s_nop 0
	v_add_u32_e32 v16, s44, v20
	v_ashrrev_i32_e32 v17, 31, v16
	v_lshl_add_u64 v[16:17], v[16:17], 2, s[6:7]
	global_load_dword v16, v[16:17], off
	v_mov_b32_e32 v18, v8
	v_mov_b32_e32 v19, v12
	v_mov_b32_e32 v12, v9
	s_waitcnt vmcnt(0)
	v_fmamk_f32 v16, v16, 0x3a000000, v153
	v_cmp_gt_f32_e32 vcc, s14, v16
	v_mul_f32_e32 v17, 0x4b800000, v16
	s_nop 0
	v_cndmask_b32_e32 v16, v16, v17, vcc
	v_rsq_f32_e32 v16, v16
	s_nop 0
	v_mul_f32_e32 v17, 0x45800000, v16
	v_cndmask_b32_e32 v16, v16, v17, vcc
	v_pk_mul_f32 v[18:19], v[18:19], v[16:17] op_sel_hi:[1,0]
	s_andn2_b64 vcc, exec, s[38:39]
	v_mul_f32_e32 v8, 0xbfb8aa3b, v19
	v_exp_f32_e32 v8, v8
	s_nop 0
	v_add_f32_e32 v8, 1.0, v8
	v_rcp_f32_e32 v8, v8
	s_nop 0
	v_mul_f32_e32 v8, v19, v8
	v_mul_f32_e32 v17, v18, v8
	v_pk_mul_f32 v[8:9], v[12:13], v[16:17] op_sel_hi:[1,0]
	s_nop 0
	v_mul_f32_e32 v12, 0xbfb8aa3b, v9
	v_exp_f32_e32 v12, v12
	s_nop 0
	v_add_f32_e32 v12, 1.0, v12
	v_rcp_f32_e32 v12, v12
	s_nop 0
	v_mul_f32_e32 v9, v9, v12
	v_mul_f32_e32 v12, v8, v9
	v_mov_b32_e32 v8, v10
	v_mov_b32_e32 v9, v14
	v_pk_mul_f32 v[8:9], v[8:9], v[16:17] op_sel_hi:[1,0]
	v_mov_b32_e32 v14, v11
	v_mul_f32_e32 v10, 0xbfb8aa3b, v9
	v_exp_f32_e32 v10, v10
	s_nop 0
	v_add_f32_e32 v10, 1.0, v10
	v_rcp_f32_e32 v10, v10
	s_nop 0
	v_mul_f32_e32 v9, v9, v10
	v_mul_f32_e32 v10, v8, v9
	v_pk_mul_f32 v[8:9], v[14:15], v[16:17] op_sel_hi:[1,0]
	s_nop 0
	v_mul_f32_e32 v11, 0xbfb8aa3b, v9
	v_exp_f32_e32 v11, v11
	s_nop 0
	v_add_f32_e32 v11, 1.0, v11
	v_rcp_f32_e32 v11, v11
	s_nop 0
	v_mul_f32_e32 v9, v9, v11
	v_mul_f32_e32 v11, v8, v9
	v_mov_b32_e32 v8, v0
	v_mov_b32_e32 v9, v4
	v_pk_mul_f32 v[8:9], v[8:9], v[16:17] op_sel_hi:[1,0]
	v_mov_b32_e32 v4, v1
	v_mul_f32_e32 v0, 0xbfb8aa3b, v9
	v_exp_f32_e32 v0, v0
	s_nop 0
	v_add_f32_e32 v0, 1.0, v0
	v_rcp_f32_e32 v0, v0
	s_nop 0
	v_mul_f32_e32 v0, v9, v0
	v_mul_f32_e32 v8, v8, v0
	v_pk_mul_f32 v[0:1], v[4:5], v[16:17] op_sel_hi:[1,0]
	s_nop 0
	v_mul_f32_e32 v4, 0xbfb8aa3b, v1
	v_exp_f32_e32 v4, v4
	s_nop 0
	v_add_f32_e32 v4, 1.0, v4
	v_rcp_f32_e32 v4, v4
	s_nop 0
	v_mul_f32_e32 v1, v1, v4
	v_mul_f32_e32 v4, v0, v1
	v_mov_b32_e32 v0, v2
	v_mov_b32_e32 v1, v6
	v_pk_mul_f32 v[0:1], v[0:1], v[16:17] op_sel_hi:[1,0]
	v_mov_b32_e32 v6, v3
	v_mul_f32_e32 v2, 0xbfb8aa3b, v1
	v_exp_f32_e32 v2, v2
	s_nop 0
	v_add_f32_e32 v2, 1.0, v2
	v_rcp_f32_e32 v2, v2
	s_nop 0
	v_mul_f32_e32 v1, v1, v2
	v_mul_f32_e32 v5, v0, v1
	v_pk_mul_f32 v[0:1], v[6:7], v[16:17] op_sel_hi:[1,0]
	s_nop 0
	v_mul_f32_e32 v2, 0xbfb8aa3b, v1
	v_exp_f32_e32 v2, v2
	s_nop 0
	v_add_f32_e32 v2, 1.0, v2
	v_rcp_f32_e32 v2, v2
	s_nop 0
	v_mul_f32_e32 v1, v1, v2
	v_mul_f32_e32 v3, v0, v1
	v_cvt_pk_bf16_f32 v0, v17, v12
	v_cvt_pk_bf16_f32 v1, v10, v11
	v_cvt_pk_bf16_f32 v2, v8, v4
	v_cvt_pk_bf16_f32 v3, v5, v3
	v_mad_i64_i32 v[4:5], s[18:19], v20, s15, v[112:113]
	v_lshl_add_u64 v[4:5], v[4:5], 0, v[114:115]
	s_cmp_eq_u32 s59, 1
	s_cbranch_scc0 .Lfn_skip_st
	s_cmp_lt_u32 s99, 16
	s_cbranch_scc0 .Lfn_skip_st
	v_fmamk_f32 v212, v212, 0x3a000000, v153
	v_rsq_f32_e32 v212, v212
	s_nop 0
	v_lshlrev_b32_e32 v220, 16, v164
	v_and_b32_e32 v221, 0xffff0000, v164
	v_lshlrev_b32_e32 v222, 16, v165
	v_and_b32_e32 v223, 0xffff0000, v165
	v_lshlrev_b32_e32 v224, 16, v166
	v_and_b32_e32 v225, 0xffff0000, v166
	v_lshlrev_b32_e32 v226, 16, v167
	v_and_b32_e32 v227, 0xffff0000, v167
	v_pk_mul_f32 v[220:221], v[212:213], v[220:221] op_sel_hi:[0,1]
	v_pk_mul_f32 v[222:223], v[212:213], v[222:223] op_sel_hi:[0,1]
	v_pk_mul_f32 v[224:225], v[212:213], v[224:225] op_sel_hi:[0,1]
	v_pk_mul_f32 v[226:227], v[212:213], v[226:227] op_sel_hi:[0,1]
	v_pk_mul_f32 v[220:221], v[180:181], v[220:221]
	v_pk_mul_f32 v[222:223], v[182:183], v[222:223]
	v_pk_mul_f32 v[224:225], v[184:185], v[224:225]
	v_pk_mul_f32 v[226:227], v[186:187], v[226:227]
	global_store_dwordx4 v[218:219], v[220:223], off offset:-4096
	global_store_dwordx4 v[218:219], v[224:227], off offset:-4080
	s_nop 1
	v_lshlrev_b32_e32 v220, 16, v168
	v_and_b32_e32 v221, 0xffff0000, v168
	v_lshlrev_b32_e32 v222, 16, v169
	v_and_b32_e32 v223, 0xffff0000, v169
	v_lshlrev_b32_e32 v224, 16, v170
	v_and_b32_e32 v225, 0xffff0000, v170
	v_lshlrev_b32_e32 v226, 16, v171
	v_and_b32_e32 v227, 0xffff0000, v171
	v_pk_mul_f32 v[220:221], v[212:213], v[220:221] op_sel_hi:[0,1]
	v_pk_mul_f32 v[222:223], v[212:213], v[222:223] op_sel_hi:[0,1]
	v_pk_mul_f32 v[224:225], v[212:213], v[224:225] op_sel_hi:[0,1]
	v_pk_mul_f32 v[226:227], v[212:213], v[226:227] op_sel_hi:[0,1]
	v_pk_mul_f32 v[220:221], v[188:189], v[220:221]
	v_pk_mul_f32 v[222:223], v[190:191], v[222:223]
	v_pk_mul_f32 v[224:225], v[192:193], v[224:225]
	v_pk_mul_f32 v[226:227], v[194:195], v[226:227]
	global_store_dwordx4 v[218:219], v[220:223], off offset:-2048
	global_store_dwordx4 v[218:219], v[224:227], off offset:-2032
	s_nop 1
	v_lshlrev_b32_e32 v220, 16, v172
	v_and_b32_e32 v221, 0xffff0000, v172
	v_lshlrev_b32_e32 v222, 16, v173
	v_and_b32_e32 v223, 0xffff0000, v173
	v_lshlrev_b32_e32 v224, 16, v174
	v_and_b32_e32 v225, 0xffff0000, v174
	v_lshlrev_b32_e32 v226, 16, v175
	v_and_b32_e32 v227, 0xffff0000, v175
	v_pk_mul_f32 v[220:221], v[212:213], v[220:221] op_sel_hi:[0,1]
	v_pk_mul_f32 v[222:223], v[212:213], v[222:223] op_sel_hi:[0,1]
	v_pk_mul_f32 v[224:225], v[212:213], v[224:225] op_sel_hi:[0,1]
	v_pk_mul_f32 v[226:227], v[212:213], v[226:227] op_sel_hi:[0,1]
	v_pk_mul_f32 v[220:221], v[196:197], v[220:221]
	v_pk_mul_f32 v[222:223], v[198:199], v[222:223]
	v_pk_mul_f32 v[224:225], v[200:201], v[224:225]
	v_pk_mul_f32 v[226:227], v[202:203], v[226:227]
	global_store_dwordx4 v[218:219], v[220:223], off offset:0
	global_store_dwordx4 v[218:219], v[224:227], off offset:16
	s_nop 1
	v_lshlrev_b32_e32 v220, 16, v176
	v_and_b32_e32 v221, 0xffff0000, v176
	v_lshlrev_b32_e32 v222, 16, v177
	v_and_b32_e32 v223, 0xffff0000, v177
	v_lshlrev_b32_e32 v224, 16, v178
	v_and_b32_e32 v225, 0xffff0000, v178
	v_lshlrev_b32_e32 v226, 16, v179
	v_and_b32_e32 v227, 0xffff0000, v179
	v_pk_mul_f32 v[220:221], v[212:213], v[220:221] op_sel_hi:[0,1]
	v_pk_mul_f32 v[222:223], v[212:213], v[222:223] op_sel_hi:[0,1]
	v_pk_mul_f32 v[224:225], v[212:213], v[224:225] op_sel_hi:[0,1]
	v_pk_mul_f32 v[226:227], v[212:213], v[226:227] op_sel_hi:[0,1]
	v_pk_mul_f32 v[220:221], v[204:205], v[220:221]
	v_pk_mul_f32 v[222:223], v[206:207], v[222:223]
	v_pk_mul_f32 v[224:225], v[208:209], v[224:225]
	v_pk_mul_f32 v[226:227], v[210:211], v[226:227]
	global_store_dwordx4 v[218:219], v[220:223], off offset:2048
	global_store_dwordx4 v[218:219], v[224:227], off offset:2064
	s_nop 1
	s_add_u32 s99, s99, 1
.Lfn_skip_st:
	s_mov_b64 s[18:19], -1
	global_store_dwordx4 v[4:5], v[0:3], off nt
	s_cbranch_vccnz .LBB0_686
	s_andn2_b64 vcc, exec, s[40:41]
	s_cbranch_vccnz .LBB0_685
	s_barrier
	s_branch .LBB0_685
